# H-tile prefetch (4 dword loads per thread) at unit start of out-proj/down-proj GEMMs
# baseline (speedup 1.0000x reference)
.LBB0_1369:
	s_ashr_i32 s55, s54, 31
	s_lshl_b64 s[56:57], s[54:55], 20
	s_add_u32 s56, s10, s56
	s_addc_u32 s57, s86, s57
	s_and_b64 s[58:59], s[40:41], exec
	s_cselect_b32 s55, s57, s61
	s_cselect_b32 s81, s56, s60
	s_ashr_i32 s53, s52, 31
	s_lshl_b64 s[58:59], s[52:53], 20
	s_add_u32 s58, s87, s58
	s_addc_u32 s59, s88, s59
	s_and_b64 s[64:65], s[40:41], exec
	s_cselect_b32 s53, s59, s63
	s_cselect_b32 s82, s58, s62
	v_mbcnt_lo_u32_b32 v0, -1, 0
	v_mbcnt_hi_u32_b32 v0, -1, v0
	v_lshl_or_b32 v0, s93, 6, v0
	v_and_b32_e32 v1, 7, v0
	v_lshrrev_b32_e32 v0, 3, v0
	v_lshlrev_b32_e32 v0, 13, v0
	v_lshl_or_b32 v0, v1, 7, v0
	v_lshl_add_u32 v0, s80, 21, v0
	v_lshl_add_u32 v0, s24, 10, v0
	global_load_dword v220, v0, s[44:45]
	v_add_u32_e32 v1, 0x80000, v0
	global_load_dword v221, v1, s[44:45]
	v_add_u32_e32 v0, 0x100000, v0
	global_load_dword v222, v0, s[44:45]
	v_add_u32_e32 v1, 0x100000, v1
	global_load_dword v223, v1, s[44:45]
	s_add_u32 s60, s60, 0x80080
	s_addc_u32 s61, s61, 0
	s_add_u32 s83, s62, 0x100
	v_mov_b32_e32 v0, 0
	s_addc_u32 s27, s63, 0
	s_mov_b32 s71, -2
	v_mov_b32_e32 v1, v0
	v_mov_b32_e32 v2, v0
	v_mov_b32_e32 v3, v0
	v_mov_b32_e32 v4, v0
	v_mov_b32_e32 v5, v0
	v_mov_b32_e32 v6, v0
	v_mov_b32_e32 v7, v0
	v_mov_b32_e32 v16, v0
	v_mov_b32_e32 v17, v0
	v_mov_b32_e32 v18, v0
	v_mov_b32_e32 v19, v0
	v_mov_b32_e32 v20, v0
	v_mov_b32_e32 v21, v0
	v_mov_b32_e32 v22, v0
	v_mov_b32_e32 v23, v0
	v_mov_b32_e32 v48, v0
	v_mov_b32_e32 v49, v0
	v_mov_b32_e32 v50, v0
	v_mov_b32_e32 v51, v0
	v_mov_b32_e32 v52, v0
	v_mov_b32_e32 v53, v0
	v_mov_b32_e32 v54, v0
	v_mov_b32_e32 v55, v0
	v_mov_b32_e32 v80, v0
	v_mov_b32_e32 v81, v0
	v_mov_b32_e32 v82, v0
	v_mov_b32_e32 v83, v0
	v_mov_b32_e32 v84, v0
	v_mov_b32_e32 v85, v0
	v_mov_b32_e32 v86, v0
	v_mov_b32_e32 v87, v0
	v_mov_b32_e32 v8, v0
	v_mov_b32_e32 v9, v0
	v_mov_b32_e32 v10, v0
	v_mov_b32_e32 v11, v0
	v_mov_b32_e32 v12, v0
	v_mov_b32_e32 v13, v0
	v_mov_b32_e32 v14, v0
	v_mov_b32_e32 v15, v0
	v_mov_b32_e32 v24, v0
	v_mov_b32_e32 v25, v0
	v_mov_b32_e32 v26, v0
	v_mov_b32_e32 v27, v0
	v_mov_b32_e32 v28, v0
	v_mov_b32_e32 v29, v0
	v_mov_b32_e32 v30, v0
	v_mov_b32_e32 v31, v0
	v_mov_b32_e32 v72, v0
	v_mov_b32_e32 v73, v0
	v_mov_b32_e32 v74, v0
	v_mov_b32_e32 v75, v0
	v_mov_b32_e32 v76, v0
	v_mov_b32_e32 v77, v0
	v_mov_b32_e32 v78, v0
	v_mov_b32_e32 v79, v0
	v_mov_b32_e32 v88, v0
	v_mov_b32_e32 v89, v0
	v_mov_b32_e32 v90, v0
	v_mov_b32_e32 v91, v0
	v_mov_b32_e32 v92, v0
	v_mov_b32_e32 v93, v0
	v_mov_b32_e32 v94, v0
	v_mov_b32_e32 v95, v0
	v_mov_b32_e32 v96, v0
	v_mov_b32_e32 v97, v0
	v_mov_b32_e32 v98, v0
	v_mov_b32_e32 v99, v0
	v_mov_b32_e32 v100, v0
	v_mov_b32_e32 v101, v0
	v_mov_b32_e32 v102, v0
	v_mov_b32_e32 v103, v0
	v_mov_b32_e32 v112, v0
	v_mov_b32_e32 v113, v0
	v_mov_b32_e32 v114, v0
	v_mov_b32_e32 v115, v0
	v_mov_b32_e32 v116, v0
	v_mov_b32_e32 v117, v0
	v_mov_b32_e32 v118, v0
	v_mov_b32_e32 v119, v0
	v_mov_b32_e32 v128, v0
	v_mov_b32_e32 v129, v0
	v_mov_b32_e32 v130, v0
	v_mov_b32_e32 v131, v0
	v_mov_b32_e32 v132, v0
	v_mov_b32_e32 v133, v0
	v_mov_b32_e32 v134, v0
	v_mov_b32_e32 v135, v0
	v_mov_b32_e32 v144, v0
	v_mov_b32_e32 v145, v0
	v_mov_b32_e32 v146, v0
	v_mov_b32_e32 v147, v0
	v_mov_b32_e32 v148, v0
	v_mov_b32_e32 v149, v0
	v_mov_b32_e32 v150, v0
	v_mov_b32_e32 v151, v0
	v_mov_b32_e32 v104, v0
	v_mov_b32_e32 v105, v0
	v_mov_b32_e32 v106, v0
	v_mov_b32_e32 v107, v0
	v_mov_b32_e32 v108, v0
	v_mov_b32_e32 v109, v0
	v_mov_b32_e32 v110, v0
	v_mov_b32_e32 v111, v0
	v_mov_b32_e32 v120, v0
	v_mov_b32_e32 v121, v0
	v_mov_b32_e32 v122, v0
	v_mov_b32_e32 v123, v0
	v_mov_b32_e32 v124, v0
	v_mov_b32_e32 v125, v0
	v_mov_b32_e32 v126, v0
	v_mov_b32_e32 v127, v0
	v_mov_b32_e32 v136, v0
	v_mov_b32_e32 v137, v0
	v_mov_b32_e32 v138, v0
	v_mov_b32_e32 v139, v0
	v_mov_b32_e32 v140, v0
	v_mov_b32_e32 v141, v0
	v_mov_b32_e32 v142, v0
	v_mov_b32_e32 v143, v0
	v_mov_b32_e32 v152, v0
	v_mov_b32_e32 v153, v0
	v_mov_b32_e32 v154, v0
	v_mov_b32_e32 v155, v0
	v_mov_b32_e32 v156, v0
	v_mov_b32_e32 v157, v0
	v_mov_b32_e32 v158, v0
	v_mov_b32_e32 v159, v0

.LBB0_1695:
	v_mbcnt_lo_u32_b32 v0, -1, 0
	v_mbcnt_hi_u32_b32 v0, -1, v0
	v_lshl_or_b32 v0, s93, 6, v0
	v_and_b32_e32 v1, 7, v0
	v_lshrrev_b32_e32 v0, 3, v0
	v_lshlrev_b32_e32 v0, 13, v0
	v_lshl_or_b32 v0, v1, 7, v0
	v_lshl_add_u32 v0, s83, 21, v0
	v_lshl_add_u32 v0, s24, 10, v0
	global_load_dword v220, v0, s[46:47]
	v_add_u32_e32 v1, 0x80000, v0
	global_load_dword v221, v1, s[46:47]
	v_add_u32_e32 v0, 0x100000, v0
	global_load_dword v222, v0, s[46:47]
	v_add_u32_e32 v1, 0x100000, v1
	global_load_dword v223, v1, s[46:47]
	s_add_u32 s27, s60, 0x100
	v_mov_b32_e32 v0, 0
	s_addc_u32 s71, s61, 0
	s_mov_b32 s79, -2
	v_mov_b32_e32 v1, v0
	v_mov_b32_e32 v2, v0
	v_mov_b32_e32 v3, v0
	v_mov_b32_e32 v4, v0
	v_mov_b32_e32 v5, v0
	v_mov_b32_e32 v6, v0
	v_mov_b32_e32 v7, v0
	v_mov_b32_e32 v16, v0
	v_mov_b32_e32 v17, v0
	v_mov_b32_e32 v18, v0
	v_mov_b32_e32 v19, v0
	v_mov_b32_e32 v20, v0
	v_mov_b32_e32 v21, v0
	v_mov_b32_e32 v22, v0
	v_mov_b32_e32 v23, v0
	v_mov_b32_e32 v32, v0
	v_mov_b32_e32 v33, v0
	v_mov_b32_e32 v34, v0
	v_mov_b32_e32 v35, v0
	v_mov_b32_e32 v36, v0
	v_mov_b32_e32 v37, v0
	v_mov_b32_e32 v38, v0
	v_mov_b32_e32 v39, v0
	v_mov_b32_e32 v52, v0
	v_mov_b32_e32 v53, v0
	v_mov_b32_e32 v54, v0
	v_mov_b32_e32 v55, v0
	v_mov_b32_e32 v56, v0
	v_mov_b32_e32 v57, v0
	v_mov_b32_e32 v58, v0
	v_mov_b32_e32 v59, v0
	v_mov_b32_e32 v8, v0
	v_mov_b32_e32 v9, v0
	v_mov_b32_e32 v10, v0
	v_mov_b32_e32 v11, v0
	v_mov_b32_e32 v12, v0
	v_mov_b32_e32 v13, v0
	v_mov_b32_e32 v14, v0
	v_mov_b32_e32 v15, v0
	v_mov_b32_e32 v24, v0
	v_mov_b32_e32 v25, v0
	v_mov_b32_e32 v26, v0
	v_mov_b32_e32 v27, v0
	v_mov_b32_e32 v28, v0
	v_mov_b32_e32 v29, v0
	v_mov_b32_e32 v30, v0
	v_mov_b32_e32 v31, v0
	v_mov_b32_e32 v40, v0
	v_mov_b32_e32 v41, v0
	v_mov_b32_e32 v42, v0
	v_mov_b32_e32 v43, v0
	v_mov_b32_e32 v44, v0
	v_mov_b32_e32 v45, v0
	v_mov_b32_e32 v46, v0
	v_mov_b32_e32 v47, v0
	v_mov_b32_e32 v88, v0
	v_mov_b32_e32 v89, v0
	v_mov_b32_e32 v90, v0
	v_mov_b32_e32 v91, v0
	v_mov_b32_e32 v92, v0
	v_mov_b32_e32 v93, v0
	v_mov_b32_e32 v94, v0
	v_mov_b32_e32 v95, v0
	v_mov_b32_e32 v96, v0
	v_mov_b32_e32 v97, v0
	v_mov_b32_e32 v98, v0
	v_mov_b32_e32 v99, v0
	v_mov_b32_e32 v100, v0
	v_mov_b32_e32 v101, v0
	v_mov_b32_e32 v102, v0
	v_mov_b32_e32 v103, v0
	v_mov_b32_e32 v112, v0
	v_mov_b32_e32 v113, v0
	v_mov_b32_e32 v114, v0
	v_mov_b32_e32 v115, v0
	v_mov_b32_e32 v116, v0
	v_mov_b32_e32 v117, v0
	v_mov_b32_e32 v118, v0
	v_mov_b32_e32 v119, v0
	v_mov_b32_e32 v128, v0
	v_mov_b32_e32 v129, v0
	v_mov_b32_e32 v130, v0
	v_mov_b32_e32 v131, v0
	v_mov_b32_e32 v132, v0
	v_mov_b32_e32 v133, v0
	v_mov_b32_e32 v134, v0
	v_mov_b32_e32 v135, v0
	v_mov_b32_e32 v144, v0
	v_mov_b32_e32 v145, v0
	v_mov_b32_e32 v146, v0
	v_mov_b32_e32 v147, v0
	v_mov_b32_e32 v148, v0
	v_mov_b32_e32 v149, v0
	v_mov_b32_e32 v150, v0
	v_mov_b32_e32 v151, v0
	v_mov_b32_e32 v104, v0
	v_mov_b32_e32 v105, v0
	v_mov_b32_e32 v106, v0
	v_mov_b32_e32 v107, v0
	v_mov_b32_e32 v108, v0
	v_mov_b32_e32 v109, v0
	v_mov_b32_e32 v110, v0
	v_mov_b32_e32 v111, v0
	v_mov_b32_e32 v120, v0
	v_mov_b32_e32 v121, v0
	v_mov_b32_e32 v122, v0
	v_mov_b32_e32 v123, v0
	v_mov_b32_e32 v124, v0
	v_mov_b32_e32 v125, v0
	v_mov_b32_e32 v126, v0
	v_mov_b32_e32 v127, v0
	v_mov_b32_e32 v136, v0
	v_mov_b32_e32 v137, v0
	v_mov_b32_e32 v138, v0
	v_mov_b32_e32 v139, v0
	v_mov_b32_e32 v140, v0
	v_mov_b32_e32 v141, v0
	v_mov_b32_e32 v142, v0
	v_mov_b32_e32 v143, v0
	v_mov_b32_e32 v152, v0
	v_mov_b32_e32 v153, v0
	v_mov_b32_e32 v154, v0
	v_mov_b32_e32 v155, v0
	v_mov_b32_e32 v156, v0
	v_mov_b32_e32 v157, v0
	v_mov_b32_e32 v158, v0
	v_mov_b32_e32 v159, v0
